# batched LDS reads in HGRN column-sum loops (same summation order)
# speedup vs baseline: 1.0050x; 1.0050x over previous
; DEV float bf2f(unsigned short b) { return __uint_as_float(((unsigned)b) << 16); }
; DEV void phase_hg_c3(const Params& p, char* smem) {
;     ...
;       {
;         float t = 0.f;
; #pragma unroll 8
;         for (int s = 0; s < 32; s++) t += bf2f(Kin[(half * 32 + s) * 144 + k]);
;         tot[half * 128 + k] = t;
;       }
;       __syncthreads();
;       if (dir == 0) {
;         float run = half ? tot[k] : 0.f;
.LBB0_280:
	v_add_u32_e32 v108, s6, v148
	ds_read_u16 v109, v108
	ds_read_u16 v172, v108 offset:288
	ds_read_u16 v173, v108 offset:576
	ds_read_u16 v174, v108 offset:864
	ds_read_u16 v175, v108 offset:1152
	ds_read_u16 v176, v108 offset:1440
	ds_read_u16 v177, v108 offset:1728
	ds_read_u16 v108, v108 offset:2016
	s_addk_i32 s6, 0x900
	s_cmpk_eq_i32 s6, 0x2400
	s_waitcnt lgkmcnt(7)
	v_lshlrev_b32_e32 v109, 16, v109
	v_add_f32_e32 v0, v0, v109
	s_waitcnt lgkmcnt(6)
	v_lshlrev_b32_e32 v172, 16, v172
	v_add_f32_e32 v0, v0, v172
	s_waitcnt lgkmcnt(5)
	v_lshlrev_b32_e32 v173, 16, v173
	v_add_f32_e32 v0, v0, v173
	s_waitcnt lgkmcnt(4)
	v_lshlrev_b32_e32 v174, 16, v174
	v_add_f32_e32 v0, v0, v174
	s_waitcnt lgkmcnt(3)
	v_lshlrev_b32_e32 v175, 16, v175
	v_add_f32_e32 v0, v0, v175
	s_waitcnt lgkmcnt(2)
	v_lshlrev_b32_e32 v176, 16, v176
	v_add_f32_e32 v0, v0, v176
	s_waitcnt lgkmcnt(1)
	v_lshlrev_b32_e32 v177, 16, v177
	v_add_f32_e32 v0, v0, v177
	s_waitcnt lgkmcnt(0)
	v_lshlrev_b32_e32 v108, 16, v108
	v_add_f32_e32 v0, v0, v108
	s_cbranch_scc0 .LBB0_280
	s_mov_b64 s[6:7], -1
	s_and_b64 vcc, exec, s[78:79]
	ds_write_b32 v127, v0 offset:57344
	s_waitcnt lgkmcnt(0)
	s_barrier
	s_cbranch_vccz .LBB0_287
	v_mov_b32_e32 v0, 0
	s_mov_b64 s[6:7], exec
	v_readlane_b32 s14, v255, 0
	v_readlane_b32 s15, v255, 1
	s_and_b64 s[14:15], s[6:7], s[14:15]
	s_mov_b64 exec, s[14:15]
	ds_read_b32 v0, v127 offset:57856
	s_or_b64 exec, exec, s[6:7]
	s_movk_i32 s6, 0x1f80

; DEV float bf2f(unsigned short b) { return __uint_as_float(((unsigned)b) << 16); }
; DEV void phase_hg_c1(const Params& p, char* smem) {
;     ...
;       {
;         float t = 0.f;
; #pragma unroll 8
;         for (int s = 0; s < 32; s++) t += bf2f(stg[(half * 32 + s) * 144 + k]);
;         tot[half * 128 + k] = t;
;       }
;       __syncthreads();
;       {
;         const float tot0 = tot[k], total = tot0 + tot[128 + k];
;         float run = half ? tot0 : 0.f;
;         float lfr[32];
; #pragma unroll
;         for (int s = 0; s < 32; s++) lfr[s] = bf2f(stg[(half * 32 + s) * 144 + k]);
.LBB0_310:
	v_add_u32_e32 v21, s9, v17
	ds_read_u16 v30, v21
	ds_read_u16 v154, v21 offset:288
	ds_read_u16 v155, v21 offset:576
	ds_read_u16 v156, v21 offset:864
	ds_read_u16 v157, v21 offset:1152
	ds_read_u16 v158, v21 offset:1440
	ds_read_u16 v159, v21 offset:1728
	ds_read_u16 v21, v21 offset:2016
	s_addk_i32 s9, 0x900
	s_cmpk_eq_i32 s9, 0x2400
	s_waitcnt lgkmcnt(7)
	v_lshlrev_b32_e32 v30, 16, v30
	v_add_f32_e32 v19, v19, v30
	s_waitcnt lgkmcnt(6)
	v_lshlrev_b32_e32 v154, 16, v154
	v_add_f32_e32 v19, v19, v154
	s_waitcnt lgkmcnt(5)
	v_lshlrev_b32_e32 v155, 16, v155
	v_add_f32_e32 v19, v19, v155
	s_waitcnt lgkmcnt(4)
	v_lshlrev_b32_e32 v156, 16, v156
	v_add_f32_e32 v19, v19, v156
	s_waitcnt lgkmcnt(3)
	v_lshlrev_b32_e32 v157, 16, v157
	v_add_f32_e32 v19, v19, v157
	s_waitcnt lgkmcnt(2)
	v_lshlrev_b32_e32 v158, 16, v158
	v_add_f32_e32 v19, v19, v158
	s_waitcnt lgkmcnt(1)
	v_lshlrev_b32_e32 v159, 16, v159
	v_add_f32_e32 v19, v19, v159
	s_waitcnt lgkmcnt(0)
	v_lshlrev_b32_e32 v21, 16, v21
	v_add_f32_e32 v19, v19, v21
	s_cbranch_scc0 .LBB0_310
	v_lshlrev_b32_e32 v17, 1, v33
	v_add3_u32 v17, s8, v17, v52
	ds_write_b32 v3, v19 offset:61440
	s_waitcnt lgkmcnt(0)
	s_barrier
	ds_read2st64_b32 v[30:31], v8 offset0:240 offset1:242
	ds_read_u16 v19, v17
	ds_read_u16 v21, v17 offset:288
	ds_read_u16 v54, v17 offset:576
	ds_read_u16 v55, v17 offset:864
	ds_read_u16 v56, v17 offset:1152
	ds_read_u16 v57, v17 offset:1440
	ds_read_u16 v58, v17 offset:1728
	ds_read_u16 v59, v17 offset:2016
	ds_read_u16 v60, v17 offset:2304
	ds_read_u16 v61, v17 offset:2592
	ds_read_u16 v62, v17 offset:2880
	ds_read_u16 v63, v17 offset:3168
	ds_read_u16 v64, v17 offset:3456
	ds_read_u16 v65, v17 offset:3744
	ds_read_u16 v66, v17 offset:4032
	ds_read_u16 v67, v17 offset:4320
	ds_read_u16 v68, v17 offset:4608
	ds_read_u16 v69, v17 offset:4896
	ds_read_u16 v70, v17 offset:5184
	ds_read_u16 v71, v17 offset:5472
	ds_read_u16 v72, v17 offset:5760
	ds_read_u16 v73, v17 offset:6048
	ds_read_u16 v74, v17 offset:6336
	ds_read_u16 v75, v17 offset:6624
	ds_read_u16 v76, v17 offset:6912
	ds_read_u16 v77, v17 offset:7200
	ds_read_u16 v78, v17 offset:7488
	ds_read_u16 v79, v17 offset:7776
	ds_read_u16 v80, v17 offset:8064
	ds_read_u16 v81, v17 offset:8352
	ds_read_u16 v82, v17 offset:8640
	ds_read_u16 v83, v17 offset:8928
	s_and_b64 vcc, exec, s[0:1]
	s_cbranch_vccz .LBB0_313
	s_waitcnt lgkmcnt(0)
	s_barrier
